# v34 + P8 norm2 next-row software prefetch into dead VGPRs v160-175 (loads issued before current row stores, loop-top vmcnt(8))
# speedup vs baseline: 1.0033x; 1.0013x over previous
; __device__ __forceinline__ float bf_lo(unsigned w) { return __uint_as_float(w << 16); }
; __device__ __forceinline__ float bf_hi(unsigned w) { return __uint_as_float(w & 0xffff0000u); }
; __device__ __forceinline__ void phase_norm(Frame& F, const Params& p, int which) {
;     ...
;     const int gw = F.bx * NWAVES + F.wave, NGW = F.G * NWAVES;
;     const int nrows = which == 0 ? NTOK + NCTXT : NTOK;
;     for (int m = gw; m < nrows; m += NGW) {
;         const float* xrow; bf16* orow; int r;
;         if (which == 0) {
;             if (m < NTOK) { xrow = p.in[0] + (size_t)m * D; orow = (bf16*)(F.ws + WS_NBUF) + (size_t)m * D; r = m >> 14; }
;             else { xrow = p.in[2] + (size_t)(m - NTOK) * D; orow = (bf16*)(F.ws + WS_NCTX) + (size_t)(m - NTOK) * D; r = 2; }
;         } else { xrow = p.in[0] + (size_t)m * D; orow = (bf16*)(F.ws + WS_NBUF) + (size_t)m * D; r = m >> 14; }
;         const f32x4* xr = (const f32x4*)xrow + F.lane;
;         f32x4 v[8]; float s = 0.f;
;         if (which == 1) {
;             const u32x2* mr = (const u32x2*)((const bf16*)(F.ws + WS_MIX) + (size_t)m * D) + F.lane;
; #pragma unroll
;             for (int j = 0; j < 8; ++j) { const u32x2 mw = mr[64 * j]; v[j] = (f32x4){bf_lo(mw.x), bf_hi(mw.x), bf_lo(mw.y), bf_hi(mw.y)}; }
.LBB0_1782:
	s_or_b64 exec, exec, s[6:7]
	s_cmp_lt_i32 s60, 0x8000
	s_cselect_b64 s[88:89], -1, 0
	s_cmpk_gt_i32 s60, 0x7fff
	s_waitcnt lgkmcnt(0)
	s_barrier
	s_cbranch_scc1 .LBB0_1789
	s_add_u32 s12, s56, 0x1c100000
	s_addc_u32 s13, s57, 0
	s_lshl_b32 s14, s2, 4
	s_lshl_b32 s15, s95, 1
	v_lshlrev_b32_e32 v0, 2, v4
	s_add_i32 s15, s15, s14
	s_ashr_i32 s61, s60, 31
	v_xor_b32_e32 v10, 4, v0
	v_xor_b32_e32 v11, 8, v0
	v_xor_b32_e32 v12, 16, v0
	v_xor_b32_e32 v13, 32, v0
	v_xor_b32_e32 v14, 64, v0
	v_xor_b32_e32 v15, 0x80, v0
	v_add_u32_e32 v0, s15, v4
	s_lshl_b32 s22, s58, 4
	s_lshl_b64 s[14:15], s[60:61], 2
	s_add_u32 s23, s14, 0x1c000000
	v_ashrrev_i32_e32 v5, 31, v4
	s_addc_u32 s24, s15, 0
	s_ashr_i32 s55, s54, 31
	s_lshl_b64 s[16:17], s[60:61], 12
	s_lshl_b64 s[18:19], s[60:61], 11
	v_lshl_add_u32 v16, v4, 4, 0
	v_cmp_eq_u32_e64 s[6:7], 0, v4
	v_cmp_gt_i32_e64 s[8:9], 2, v4
	s_lshl_b64 s[14:15], s[54:55], 2
	v_lshl_add_u64 v[2:3], v[4:5], 3, s[16:17]
	s_lshl_b64 s[16:17], s[54:55], 12
	v_lshl_add_u64 v[4:5], v[4:5], 2, s[18:19]
	s_lshl_b64 s[18:19], s[54:55], 11
	v_mov_b32_e32 v17, 0x358637bd
	s_mov_b32 s25, 0x800000
	s_mov_b32 s26, 0x42fe0000
	s_mov_b32 s27, 0x40c0c00
	s_brev_b32 s28, 24
	v_mov_b32_e32 v18, 0
	s_mov_b32 s29, s60
	v_lshl_add_u64 v[6:7], s[56:57], 0, v[2:3]
	v_add_co_u32_e32 v6, vcc, 0x2e000000, v6
	s_nop 1
	v_addc_co_u32_e32 v7, vcc, 0, v7, vcc
	global_load_dwordx2 v[160:161], v[6:7], off offset:1536
	global_load_dwordx2 v[162:163], v[6:7], off offset:3584
	global_load_dwordx2 v[164:165], v[6:7], off
	global_load_dwordx2 v[166:167], v[6:7], off offset:512
	global_load_dwordx2 v[168:169], v[6:7], off offset:1024
	global_load_dwordx2 v[170:171], v[6:7], off offset:2048
	global_load_dwordx2 v[172:173], v[6:7], off offset:2560
	global_load_dwordx2 v[174:175], v[6:7], off offset:3072
	s_waitcnt vmcnt(0)
	s_branch .LBB0_1785

; #define LAS __attribute__((address_space(3)))
; __device__ __forceinline__ unsigned pk2(float lo, float hi) { return f2bf(lo) | (f2bf(hi) << 16); }
; __device__ __forceinline__ float bf_lo(unsigned w) { return __uint_as_float(w << 16); }
; __device__ __forceinline__ float bf_hi(unsigned w) { return __uint_as_float(w & 0xffff0000u); }
; __device__ __forceinline__ void phase_norm(Frame& F, const Params& p, int which) {
;     ...
;     for (int m = gw; m < nrows; m += NGW) {
;         const float* xrow; bf16* orow; int r;
;         if (which == 0) {
;             if (m < NTOK) { xrow = p.in[0] + (size_t)m * D; orow = (bf16*)(F.ws + WS_NBUF) + (size_t)m * D; r = m >> 14; }
;             else { xrow = p.in[2] + (size_t)(m - NTOK) * D; orow = (bf16*)(F.ws + WS_NCTX) + (size_t)(m - NTOK) * D; r = 2; }
;         } else { xrow = p.in[0] + (size_t)m * D; orow = (bf16*)(F.ws + WS_NBUF) + (size_t)m * D; r = m >> 14; }
;         const f32x4* xr = (const f32x4*)xrow + F.lane;
;         f32x4 v[8]; float s = 0.f;
;         if (which == 1) {
;             const u32x2* mr = (const u32x2*)((const bf16*)(F.ws + WS_MIX) + (size_t)m * D) + F.lane;
; #pragma unroll
;             for (int j = 0; j < 8; ++j) { const u32x2 mw = mr[64 * j]; v[j] = (f32x4){bf_lo(mw.x), bf_hi(mw.x), bf_lo(mw.y), bf_hi(mw.y)}; }
;         } else {
; #pragma unroll
;             for (int j = 0; j < 8; ++j) v[j] = xr[64 * j];
;         }
; #pragma unroll
;         for (int j = 0; j < 8; ++j) s += (v[j][0] * v[j][0] + v[j][1] * v[j][1]) + (v[j][2] * v[j][2] + v[j][3] * v[j][3]);
;         const float rstd = rsqrtf(wave_sum(s, F.lane) * (1.f / D) + 1e-6f);
;         u32x2* o8 = (u32x2*)orow + F.lane;
;         float am = 0.f;
; #pragma unroll
;         for (int j = 0; j < 8; ++j) {
;             const f32x4 g4 = *(const LAS f32x4*)(gs + r * D + 4 * F.lane + 256 * j), s4 = *(const LAS f32x4*)(sh + r * D + 4 * F.lane + 256 * j);
;             v[j] = (f32x4){v[j][0] * rstd * g4[0] + s4[0], v[j][1] * rstd * g4[1] + s4[1], v[j][2] * rstd * g4[2] + s4[2], v[j][3] * rstd * g4[3] + s4[3]};
;             if (which == 0 && m >= NTOK) { u32x2 o; o.x = pk2(v[j][0], v[j][1]); o.y = pk2(v[j][2], v[j][3]); o8[64 * j] = o; }
;             am = fmaxf(am, fmaxf(fmaxf(fabsf(v[j][0]), fabsf(v[j][1])), fmaxf(fabsf(v[j][2]), fabsf(v[j][3]))));
.LBB0_1785:
	s_waitcnt lgkmcnt(0)
	s_add_i32 s30, s29, s54
	s_cmp_lt_i32 s30, 0x8000
	s_cselect_b32 s30, s16, 0
	s_cselect_b32 s31, s17, 0
	s_waitcnt vmcnt(8)
	v_mov_b64_e32 v[20:21], v[160:161]
	v_mov_b64_e32 v[22:23], v[162:163]
	v_mov_b64_e32 v[24:25], v[164:165]
	v_mov_b64_e32 v[26:27], v[166:167]
	v_mov_b64_e32 v[28:29], v[168:169]
	v_mov_b64_e32 v[30:31], v[170:171]
	v_mov_b64_e32 v[32:33], v[172:173]
	v_mov_b64_e32 v[34:35], v[174:175]
	v_lshl_add_u64 v[6:7], v[2:3], 0, s[30:31]
	v_lshl_add_u64 v[6:7], s[56:57], 0, v[6:7]
	v_add_co_u32_e32 v6, vcc, 0x2e000000, v6
	s_ashr_i32 s20, s29, 3
	s_nop 0
	v_addc_co_u32_e32 v7, vcc, 0, v7, vcc
	global_load_dwordx2 v[160:161], v[6:7], off offset:1536
	global_load_dwordx2 v[162:163], v[6:7], off offset:3584
	global_load_dwordx2 v[164:165], v[6:7], off
	global_load_dwordx2 v[166:167], v[6:7], off offset:512
	global_load_dwordx2 v[168:169], v[6:7], off offset:1024
	global_load_dwordx2 v[170:171], v[6:7], off offset:2048
	global_load_dwordx2 v[172:173], v[6:7], off offset:2560
	global_load_dwordx2 v[174:175], v[6:7], off offset:3072
	s_lshl_b32 s20, s20, 2
	s_and_b32 s20, s20, 0xffffe000
	v_lshlrev_b32_e32 v9, 16, v20
	v_lshlrev_b32_e32 v7, 16, v22
	v_and_b32_e32 v41, 0xffff0000, v24
	v_and_b32_e32 v43, 0xffff0000, v25
	v_lshlrev_b32_e32 v40, 16, v24
	v_lshlrev_b32_e32 v42, 16, v25
	v_and_b32_e32 v47, 0xffff0000, v27
	v_and_b32_e32 v46, 0xffff0000, v26
	v_and_b32_e32 v49, 0xffff0000, v28
	v_mul_f32_e32 v6, v43, v43
	v_mul_f32_e32 v8, v41, v41
	v_and_b32_e32 v1, 0xffff0000, v20
	v_lshlrev_b32_e32 v19, 16, v21
	v_and_b32_e32 v66, 0xffff0000, v21
	v_and_b32_e32 v67, 0xffff0000, v22
	v_lshlrev_b32_e32 v68, 16, v23
	v_and_b32_e32 v69, 0xffff0000, v23
	v_lshlrev_b32_e32 v45, 16, v27
	v_lshlrev_b32_e32 v44, 16, v26
	v_lshlrev_b32_e32 v48, 16, v28
	v_and_b32_e32 v51, 0xffff0000, v29
	v_lshlrev_b32_e32 v60, 16, v34
	v_and_b32_e32 v61, 0xffff0000, v34
	v_lshlrev_b32_e32 v62, 16, v35
	v_and_b32_e32 v63, 0xffff0000, v35
	v_pk_mul_f32 v[20:21], v[46:47], v[46:47]
	v_mov_b32_e32 v23, v9
	v_mul_f32_e32 v22, v49, v49
	v_pk_fma_f32 v[34:35], v[42:43], v[42:43], v[6:7] op_sel_hi:[1,1,0]
	v_pk_fma_f32 v[36:37], v[40:41], v[40:41], v[8:9] op_sel_hi:[1,1,0]
	v_lshlrev_b32_e32 v50, 16, v29
	v_mul_f32_e32 v24, v51, v51
	v_mov_b32_e32 v25, v7
	v_pk_fma_f32 v[20:21], v[44:45], v[44:45], v[20:21]
	v_pk_fma_f32 v[38:39], v[48:49], v[48:49], v[22:23] op_sel_hi:[1,1,0]
	v_mov_b32_e32 v8, v36
	v_mov_b32_e32 v22, v34
	v_mul_f32_e32 v70, v1, v1
	v_mul_f32_e32 v71, v19, v19
	v_mul_f32_e32 v72, v66, v66
	v_pk_fma_f32 v[64:65], v[50:51], v[50:51], v[24:25] op_sel_hi:[1,1,0]
	v_pk_add_f32 v[34:35], v[36:37], v[34:35]
	v_pk_add_f32 v[20:21], v[20:21], v[20:21] op_sel:[0,1] op_sel_hi:[1,0]
	v_pk_mul_f32 v[22:23], v[8:9], v[22:23]
	v_and_b32_e32 v55, 0xffff0000, v31
	v_and_b32_e32 v54, 0xffff0000, v30
	v_mov_b32_e32 v39, v71
	v_mov_b32_e32 v65, v72
	v_mov_b32_e32 v21, v70
	v_mov_b32_e32 v35, v23
	v_lshlrev_b32_e32 v53, 16, v31
	v_lshlrev_b32_e32 v52, 16, v30
	v_pk_mul_f32 v[26:27], v[54:55], v[54:55]
	v_pk_add_f32 v[36:37], v[38:39], v[64:65]
	v_pk_add_f32 v[20:21], v[34:35], v[20:21]
	v_and_b32_e32 v59, 0xffff0000, v33
	v_and_b32_e32 v58, 0xffff0000, v32
	v_pk_fma_f32 v[26:27], v[52:53], v[52:53], v[26:27]
	v_pk_add_f32 v[20:21], v[20:21], v[36:37]
	v_lshlrev_b32_e32 v57, 16, v33
	v_lshlrev_b32_e32 v56, 16, v32
	v_pk_mul_f32 v[28:29], v[58:59], v[58:59]
	v_pk_add_f32 v[26:27], v[26:27], v[26:27] op_sel:[0,1] op_sel_hi:[1,0]
	v_pk_add_f32 v[20:21], v[20:21], v[20:21] op_sel:[0,1] op_sel_hi:[1,0]
	v_mul_f32_e32 v30, v61, v61
	v_mul_f32_e32 v32, v63, v63
	v_pk_fma_f32 v[28:29], v[56:57], v[56:57], v[28:29]
	v_mov_b32_e32 v24, v26
	v_mov_b32_e32 v6, v20
	v_mul_f32_e32 v73, v67, v67
	v_mul_f32_e32 v74, v68, v68
	v_mul_f32_e32 v75, v69, v69
	v_pk_fma_f32 v[30:31], v[60:61], v[60:61], v[30:31] op_sel_hi:[1,1,0]
	v_pk_fma_f32 v[32:33], v[62:63], v[62:63], v[32:33] op_sel_hi:[1,1,0]
	v_pk_add_f32 v[28:29], v[28:29], v[28:29] op_sel:[0,1] op_sel_hi:[1,0]
	v_pk_add_f32 v[20:21], v[20:21], v[26:27]
	v_pk_mul_f32 v[22:23], v[6:7], v[24:25]
	v_mov_b32_e32 v31, v74
	v_mov_b32_e32 v33, v75
	v_mov_b32_e32 v29, v73
	v_mov_b32_e32 v21, v23
	v_pk_add_f32 v[20:21], v[20:21], v[28:29]
	v_pk_add_f32 v[22:23], v[30:31], v[32:33]
	v_add_u32_e32 v64, s20, v16
	v_pk_add_f32 v[20:21], v[20:21], v[22:23]
	s_nop 0
	v_add_f32_e32 v6, v20, v21
	ds_bpermute_b32 v8, v10, v6
	ds_read_b128 v[20:23], v64
	ds_read_b128 v[24:27], v64 offset:1024
	ds_read_b128 v[28:31], v64 offset:24576
	ds_read_b128 v[32:35], v64 offset:25600
	ds_read_b128 v[36:39], v64 offset:2048
	s_waitcnt lgkmcnt(5)
	v_add_f32_e32 v6, v6, v8
	ds_bpermute_b32 v8, v11, v6
	s_waitcnt lgkmcnt(0)
	v_add_f32_e32 v6, v6, v8
	ds_bpermute_b32 v8, v12, v6
	s_waitcnt lgkmcnt(0)
	v_add_f32_e32 v6, v6, v8
	ds_bpermute_b32 v8, v13, v6
	s_waitcnt lgkmcnt(0)
	v_add_f32_e32 v6, v6, v8
	ds_bpermute_b32 v8, v14, v6
	s_waitcnt lgkmcnt(0)
	v_add_f32_e32 v6, v6, v8
	ds_bpermute_b32 v8, v15, v6
	s_waitcnt lgkmcnt(0)
	v_add_f32_e32 v6, v6, v8
	v_fmamk_f32 v6, v6, 0x3a000000, v17
	v_mul_f32_e32 v8, 0x4b800000, v6
	v_cmp_gt_f32_e32 vcc, s25, v6
	s_nop 1
	v_cndmask_b32_e32 v6, v6, v8, vcc
	v_rsq_f32_e32 v6, v6
	s_nop 0
	v_mul_f32_e32 v8, 0x45800000, v6
	v_cndmask_b32_e32 v6, v6, v8, vcc
	v_mul_f32_e32 v8, v6, v40
	v_mul_f32_e32 v40, v6, v41
	v_mul_f32_e32 v41, v6, v42
	v_mul_f32_e32 v42, v6, v43
	v_mul_f32_e32 v43, v6, v44
	v_mul_f32_e32 v44, v6, v46
	v_mul_f32_e32 v45, v6, v45
	v_mul_f32_e32 v46, v6, v47
	v_fma_f32 v8, v20, v8, v28
	v_fma_f32 v28, v21, v40, v29
	v_fma_f32 v29, v22, v41, v30
	v_fmac_f32_e32 v31, v23, v42
	v_fma_f32 v30, v24, v43, v32
	v_fma_f32 v32, v25, v44, v33
	v_fma_f32 v33, v26, v45, v34
	v_fmac_f32_e32 v35, v27, v46
	v_max_f32_e64 v20, |v29|, |v31|
	v_max_f32_e64 v21, |v33|, |v35|
	v_max3_f32 v24, |v8|, |v28|, v20
	v_max3_f32 v25, |v30|, |v32|, v21
	ds_read_b128 v[20:23], v64 offset:26624
	v_max3_f32 v34, v24, 0, v25
	ds_read_b128 v[24:27], v64 offset:3072
	ds_read_b128 v[40:43], v64 offset:27648
	v_mul_f32_e32 v44, v6, v48
	v_mul_f32_e32 v1, v6, v1
	s_waitcnt lgkmcnt(2)
; #define LAS __attribute__((address_space(3)))
; __device__ __forceinline__ unsigned pk2(float lo, float hi) { return f2bf(lo) | (f2bf(hi) << 16); }
; __device__ __forceinline__ float shx(float v, int o, int lane) { return __int_as_float(__builtin_amdgcn_ds_bpermute((lane ^ o) << 2, __float_as_int(v))); }
; __device__ __forceinline__ int shx(int v, int o, int lane) { return __builtin_amdgcn_ds_bpermute((lane ^ o) << 2, v); }
; __device__ __forceinline__ void phase_norm(Frame& F, const Params& p, int which) {
;     ...
; #pragma unroll
;         for (int j = 0; j < 8; ++j) {
;             const f32x4 g4 = *(const LAS f32x4*)(gs + r * D + 4 * F.lane + 256 * j), s4 = *(const LAS f32x4*)(sh + r * D + 4 * F.lane + 256 * j);
;             v[j] = (f32x4){v[j][0] * rstd * g4[0] + s4[0], v[j][1] * rstd * g4[1] + s4[1], v[j][2] * rstd * g4[2] + s4[2], v[j][3] * rstd * g4[3] + s4[3]};
;             if (which == 0 && m >= NTOK) { u32x2 o; o.x = pk2(v[j][0], v[j][1]); o.y = pk2(v[j][2], v[j][3]); o8[64 * j] = o; }
;             am = fmaxf(am, fmaxf(fmaxf(fabsf(v[j][0]), fabsf(v[j][1])), fmaxf(fabsf(v[j][2]), fabsf(v[j][3]))));
;         }
;         if (which == 0 && m < NTOK) {
; #pragma unroll
;             for (int o = 1; o < 64; o <<= 1) am = fmaxf(am, shx(am, o, F.lane));
;             const float inv = am > 0.f ? 127.f / am : 0.f;
;             unsigned* nq = (unsigned*)(F.ws + WS_NBUF8 + (size_t)m * D) + F.lane;
; #pragma unroll
;             for (int j = 0; j < 8; ++j) {
;                 const int q0 = (int)rintf(v[j][0] * inv), q1 = (int)rintf(v[j][1] * inv), q2 = (int)rintf(v[j][2] * inv), q3 = (int)rintf(v[j][3] * inv);
;                 nq[64 * j] = (unsigned)(q0 & 255) | ((unsigned)(q1 & 255) << 8) | ((unsigned)(q2 & 255) << 16) | ((unsigned)(q3 & 255) << 24);
;             }
;             if (F.lane == 0) ((float*)(F.ws + WS_RS))[m] = am * (1.f / 127.f);
;         }
;         if (which == 1) {
; #pragma unroll
;             for (int o = 1; o < 64; o <<= 1) am = fmaxf(am, shx(am, o, F.lane));
	v_fma_f32 v20, v36, v44, v20
	v_mul_f32_e32 v36, v6, v49
	v_fma_f32 v21, v37, v36, v21
	v_mul_f32_e32 v36, v6, v50
	v_fma_f32 v22, v38, v36, v22
	v_mul_f32_e32 v36, v6, v51
	s_waitcnt lgkmcnt(0)
	v_fma_f32 v41, v25, v1, v41
	v_mul_f32_e32 v1, v6, v19
	v_fmac_f32_e32 v23, v39, v36
	v_fma_f32 v19, v26, v1, v42
	v_mul_f32_e32 v1, v6, v66
	v_max_f32_e64 v36, |v22|, |v23|
	v_mul_f32_e32 v9, v6, v9
	v_fmac_f32_e32 v43, v27, v1
	v_max3_f32 v44, |v20|, |v21|, v36
	v_fma_f32 v40, v24, v9, v40
	v_max_f32_e64 v1, |v19|, |v43|
	ds_read_b128 v[24:27], v64 offset:4096
	ds_read_b128 v[36:39], v64 offset:28672
	v_max3_f32 v1, |v40|, |v41|, v1
	v_max3_f32 v1, v34, v44, v1
	ds_read_b128 v[44:47], v64 offset:5120
	ds_read_b128 v[48:51], v64 offset:29696
	v_mul_f32_e32 v9, v6, v52
	s_waitcnt lgkmcnt(2)
	v_fma_f32 v34, v24, v9, v36
	v_mul_f32_e32 v9, v6, v54
	v_fma_f32 v36, v25, v9, v37
	v_mul_f32_e32 v9, v6, v53
	v_mul_f32_e32 v24, v6, v56
	v_fma_f32 v37, v26, v9, v38
	s_waitcnt lgkmcnt(0)
	v_fma_f32 v38, v44, v24, v48
	v_mul_f32_e32 v24, v6, v58
	v_fma_f32 v42, v45, v24, v49
	v_mul_f32_e32 v24, v6, v57
	v_fma_f32 v48, v46, v24, v50
	v_mul_f32_e32 v24, v6, v59
	v_fmac_f32_e32 v51, v47, v24
	v_mul_f32_e32 v9, v6, v55
	v_max_f32_e64 v24, |v48|, |v51|
	v_fmac_f32_e32 v39, v27, v9
	v_max3_f32 v49, |v38|, |v42|, v24
	ds_read_b128 v[24:27], v64 offset:6144
	ds_read_b128 v[44:47], v64 offset:30720
	v_max_f32_e64 v9, |v37|, |v39|
	v_max3_f32 v9, |v34|, |v36|, v9
	ds_read_b128 v[52:55], v64 offset:7168
	ds_read_b128 v[56:59], v64 offset:31744
	v_max3_f32 v1, v1, v9, v49
	v_mul_f32_e32 v9, v6, v60
	s_waitcnt lgkmcnt(2)
	v_fma_f32 v24, v24, v9, v44
	v_mul_f32_e32 v9, v6, v61
	v_fma_f32 v25, v25, v9, v45
	v_mul_f32_e32 v9, v6, v62
	v_fma_f32 v26, v26, v9, v46
	v_mul_f32_e32 v9, v6, v63
	v_mul_f32_e32 v7, v6, v7
	v_fmac_f32_e32 v47, v27, v9
	s_waitcnt lgkmcnt(0)
	v_fma_f32 v27, v7, v52, v56
	v_mul_f32_e32 v7, v6, v67
	v_fma_f32 v44, v7, v53, v57
	v_mul_f32_e32 v7, v6, v68
	v_mul_f32_e32 v6, v6, v69
	v_fma_f32 v45, v7, v54, v58
	v_fmac_f32_e32 v59, v6, v55
	v_max_f32_e64 v9, |v26|, |v47|
	v_max_f32_e64 v6, |v45|, |v59|
	v_max3_f32 v9, |v24|, |v25|, v9
	v_max3_f32 v6, |v27|, |v44|, v6
	v_max3_f32 v1, v1, v9, v6
	ds_bpermute_b32 v6, v10, v1
	s_waitcnt lgkmcnt(0)
	v_max_f32_e32 v6, v6, v6
	v_max_f32_e32 v1, v1, v6
	ds_bpermute_b32 v6, v11, v1
	s_waitcnt lgkmcnt(0)
	v_max_f32_e32 v6, v6, v6
	v_max_f32_e32 v1, v1, v6
	ds_bpermute_b32 v6, v12, v1
	s_waitcnt lgkmcnt(0)
	v_max_f32_e32 v6, v6, v6
	v_max_f32_e32 v1, v1, v6
	ds_bpermute_b32 v6, v13, v1
	s_waitcnt lgkmcnt(0)
	v_max_f32_e32 v6, v6, v6
	v_max_f32_e32 v1, v1, v6
	ds_bpermute_b32 v6, v14, v1
	s_waitcnt lgkmcnt(0)
	v_max_f32_e32 v6, v6, v6
	v_max_f32_e32 v1, v1, v6
	ds_bpermute_b32 v6, v15, v1
	s_waitcnt lgkmcnt(0)
; __device__ __forceinline__ float shx(float v, int o, int lane) { return __int_as_float(__builtin_amdgcn_ds_bpermute((lane ^ o) << 2, __float_as_int(v))); }
; __device__ __forceinline__ int shx(int v, int o, int lane) { return __builtin_amdgcn_ds_bpermute((lane ^ o) << 2, v); }
; __device__ __forceinline__ void phase_norm(Frame& F, const Params& p, int which) {
;     ...
; #pragma unroll
;             for (int o = 1; o < 64; o <<= 1) am = fmaxf(am, shx(am, o, F.lane));
;             const float inv = am > 0.f ? 127.f / am : 0.f;
;             unsigned* fq = (unsigned*)(F.ws + WS_FQ + (size_t)m * D) + F.lane;
;             int qsum = 0;
; #pragma unroll
;             for (int j = 0; j < 8; ++j) {
;                 const int q0 = (int)rintf(v[j][0] * inv), q1 = (int)rintf(v[j][1] * inv), q2 = (int)rintf(v[j][2] * inv), q3 = (int)rintf(v[j][3] * inv);
;                 fq[64 * j] = (unsigned)(q0 & 255) | ((unsigned)(q1 & 255) << 8) | ((unsigned)(q2 & 255) << 16) | ((unsigned)(q3 & 255) << 24);
;                 qsum += (q0 + q1) + (q2 + q3);
;             }
; #pragma unroll
;             for (int o = 2; o < 64; o <<= 1) qsum += shx(qsum, o, F.lane);
;             if (F.lane == 0) ((float*)(F.ws + WS_FS))[m] = am * (1.f / 127.f);
	v_max_f32_e32 v6, v6, v6
	v_max_f32_e32 v1, v1, v6
	v_div_scale_f32 v6, s[20:21], v1, v1, s26
	v_rcp_f32_e32 v7, v6
	s_nop 0
	v_fma_f32 v9, -v6, v7, 1.0
	v_fmac_f32_e32 v7, v9, v7
	v_div_scale_f32 v9, vcc, s26, v1, s26
	v_mul_f32_e32 v46, v9, v7
	v_fma_f32 v49, -v6, v46, v9
	v_fmac_f32_e32 v46, v49, v7
	v_fma_f32 v6, -v6, v46, v9
	v_div_fmas_f32 v6, v6, v7, v46
	v_div_fixup_f32 v6, v6, v1, s26
	v_cmp_lt_f32_e32 vcc, 0, v1
	s_nop 1
	v_cndmask_b32_e32 v46, 0, v6, vcc
	v_mul_f32_e32 v8, v8, v46
	v_rndne_f32_e32 v8, v8
	v_cvt_i32_f32_e32 v49, v8
	v_mul_f32_e32 v8, v28, v46
	v_rndne_f32_e32 v8, v8
	v_cvt_i32_f32_e32 v28, v8
	v_mul_f32_e32 v8, v29, v46
	v_rndne_f32_e32 v8, v8
	v_cvt_i32_f32_e32 v29, v8
	v_mul_f32_e32 v8, v31, v46
	v_rndne_f32_e32 v8, v8
	v_cvt_i32_f32_e32 v31, v8
	v_lshlrev_b32_e32 v8, 8, v28
	v_lshlrev_b32_e32 v9, 16, v29
	v_lshl_add_u64 v[6:7], s[56:57], 0, v[4:5]
	v_and_b32_e32 v8, 0xff00, v8
	v_and_b32_e32 v9, 0xff0000, v9
	v_perm_b32 v50, v31, v49, s27
	v_or3_b32 v50, v50, v8, v9
	v_add_co_u32_e32 v8, vcc, s28, v6
	v_add_u32_e32 v6, v49, v28
	s_nop 0
	v_addc_co_u32_e32 v9, vcc, 0, v7, vcc
	v_mul_f32_e32 v7, v30, v46
	v_mul_f32_e32 v28, v32, v46
	v_mul_f32_e32 v30, v35, v46
	v_rndne_f32_e32 v7, v7
	v_rndne_f32_e32 v28, v28
	v_rndne_f32_e32 v30, v30
	v_cvt_i32_f32_e32 v7, v7
	v_cvt_i32_f32_e32 v28, v28
	v_cvt_i32_f32_e32 v30, v30
	v_add3_u32 v6, v6, v31, v29
	v_mul_f32_e32 v29, v33, v46
	v_rndne_f32_e32 v29, v29
	v_perm_b32 v33, v30, v7, s27
	v_add3_u32 v6, v6, v7, v28
	v_mul_f32_e32 v7, v20, v46
	v_mul_f32_e32 v20, v21, v46
	v_mul_f32_e32 v21, v22, v46
	v_mul_f32_e32 v22, v23, v46
	v_cvt_i32_f32_e32 v29, v29
	v_rndne_f32_e32 v7, v7
	v_rndne_f32_e32 v20, v20
	v_rndne_f32_e32 v22, v22
	v_cvt_i32_f32_e32 v7, v7
	v_cvt_i32_f32_e32 v20, v20
	v_rndne_f32_e32 v21, v21
	v_cvt_i32_f32_e32 v22, v22
	v_cvt_i32_f32_e32 v21, v21
	v_add3_u32 v6, v6, v30, v29
	v_lshlrev_b32_e32 v32, 16, v29
	v_lshlrev_b32_e32 v23, 8, v20
	v_perm_b32 v29, v22, v7, s27
	v_add3_u32 v6, v6, v7, v20
	v_mul_f32_e32 v7, v40, v46
	v_mul_f32_e32 v20, v41, v46
	v_lshlrev_b32_e32 v31, 8, v28
	v_lshlrev_b32_e32 v28, 16, v21
	v_add3_u32 v6, v6, v22, v21
	v_rndne_f32_e32 v7, v7
	v_rndne_f32_e32 v20, v20
	v_mul_f32_e32 v19, v19, v46
	v_mul_f32_e32 v21, v43, v46
	v_cvt_i32_f32_e32 v7, v7
	v_cvt_i32_f32_e32 v20, v20
	v_rndne_f32_e32 v19, v19
	v_rndne_f32_e32 v21, v21
	v_cvt_i32_f32_e32 v19, v19
	v_cvt_i32_f32_e32 v21, v21
	v_and_b32_e32 v23, 0xff00, v23
	v_and_b32_e32 v28, 0xff0000, v28
	v_or3_b32 v23, v29, v23, v28
	v_add3_u32 v6, v6, v7, v20
	global_store_dword v[8:9], v23, off offset:512
	v_lshlrev_b32_e32 v23, 16, v19
	v_perm_b32 v28, v21, v7, s27
	v_add3_u32 v6, v6, v21, v19
	v_mul_f32_e32 v7, v34, v46
	v_mul_f32_e32 v19, v36, v46
	v_mul_f32_e32 v21, v39, v46
	v_rndne_f32_e32 v7, v7
	v_rndne_f32_e32 v19, v19
	v_rndne_f32_e32 v21, v21
	v_lshlrev_b32_e32 v22, 8, v20
	v_cvt_i32_f32_e32 v7, v7
	v_cvt_i32_f32_e32 v19, v19
	v_mul_f32_e32 v20, v37, v46
	v_cvt_i32_f32_e32 v21, v21
	v_rndne_f32_e32 v20, v20
	v_and_b32_e32 v22, 0xff00, v22
	v_and_b32_e32 v23, 0xff0000, v23
	v_cvt_i32_f32_e32 v20, v20
	v_or3_b32 v22, v28, v22, v23
	global_store_dword v[8:9], v22, off offset:768
	v_lshlrev_b32_e32 v22, 8, v19
	v_perm_b32 v28, v21, v7, s27
	v_add3_u32 v6, v6, v7, v19
	v_mul_f32_e32 v7, v38, v46
	v_mul_f32_e32 v19, v42, v46
	v_rndne_f32_e32 v7, v7
	v_rndne_f32_e32 v19, v19
	v_lshlrev_b32_e32 v23, 16, v20
	v_cvt_i32_f32_e32 v7, v7
	v_cvt_i32_f32_e32 v19, v19
	v_and_b32_e32 v22, 0xff00, v22
	v_and_b32_e32 v23, 0xff0000, v23
	v_or3_b32 v22, v28, v22, v23
	global_store_dword v[8:9], v22, off offset:1024
	v_mul_f32_e32 v22, v48, v46
	v_mul_f32_e32 v23, v51, v46
	v_add3_u32 v6, v6, v21, v20
	v_rndne_f32_e32 v22, v22
	v_rndne_f32_e32 v23, v23
	v_lshlrev_b32_e32 v20, 8, v19
	v_add3_u32 v6, v6, v7, v19
	v_mul_f32_e32 v19, v24, v46
	v_mul_f32_e32 v21, v25, v46
	v_cvt_i32_f32_e32 v22, v22
	v_cvt_i32_f32_e32 v23, v23
	v_rndne_f32_e32 v19, v19
	v_rndne_f32_e32 v21, v21
	v_mul_f32_e32 v24, v26, v46
	v_mul_f32_e32 v25, v47, v46
	v_cvt_i32_f32_e32 v19, v19
	v_cvt_i32_f32_e32 v21, v21
	v_rndne_f32_e32 v24, v24
	v_rndne_f32_e32 v25, v25
	v_mul_f32_e32 v26, v27, v46
	v_mul_f32_e32 v27, v44, v46
	v_cvt_i32_f32_e32 v24, v24
	v_cvt_i32_f32_e32 v25, v25
	v_rndne_f32_e32 v26, v26
	v_rndne_f32_e32 v27, v27
	v_mul_f32_e32 v28, v45, v46
	v_mul_f32_e32 v29, v59, v46
	v_cvt_i32_f32_e32 v26, v26
	v_cvt_i32_f32_e32 v27, v27
	v_rndne_f32_e32 v28, v28
	v_rndne_f32_e32 v29, v29
	v_add3_u32 v6, v6, v23, v22
	v_cvt_i32_f32_e32 v28, v28
	v_cvt_i32_f32_e32 v29, v29
	v_add3_u32 v6, v6, v19, v21
	v_add3_u32 v6, v6, v25, v24
	v_add3_u32 v6, v6, v26, v27
	v_add3_u32 v6, v6, v29, v28
	ds_bpermute_b32 v30, v11, v6
	v_perm_b32 v7, v23, v7, s27
	v_lshlrev_b32_e32 v22, 16, v22
	v_and_b32_e32 v20, 0xff00, v20
	v_and_b32_e32 v22, 0xff0000, v22
	s_waitcnt lgkmcnt(0)
	v_add_u32_e32 v6, v6, v30
	ds_bpermute_b32 v23, v12, v6
	v_or3_b32 v7, v7, v20, v22
	global_store_dword v[8:9], v7, off offset:1280
	v_lshlrev_b32_e32 v7, 8, v21
	v_lshlrev_b32_e32 v21, 16, v24
	s_waitcnt lgkmcnt(0)
	v_add_u32_e32 v6, v6, v23
	ds_bpermute_b32 v20, v13, v6
	v_and_b32_e32 v7, 0xff00, v7
	v_and_b32_e32 v21, 0xff0000, v21
	v_perm_b32 v19, v25, v19, s27
	v_or3_b32 v7, v19, v7, v21
	s_waitcnt lgkmcnt(0)
	v_add_u32_e32 v6, v6, v20
	ds_bpermute_b32 v19, v14, v6
	global_store_dword v[8:9], v7, off offset:1536
	v_lshlrev_b32_e32 v7, 8, v27
	v_and_b32_e32 v20, 0xff00, v7
	v_lshlrev_b32_e32 v21, 16, v28
	s_waitcnt lgkmcnt(0)
	v_add_u32_e32 v6, v6, v19
	ds_bpermute_b32 v7, v15, v6
	v_and_b32_e32 v31, 0xff00, v31
	v_and_b32_e32 v32, 0xff0000, v32
	v_and_b32_e32 v19, 0xff0000, v21
	v_perm_b32 v21, v29, v26, s27
	v_or3_b32 v31, v33, v31, v32
	v_or3_b32 v19, v21, v20, v19
	global_store_dword v[8:9], v50, off
	global_store_dword v[8:9], v31, off offset:256
	global_store_dword v[8:9], v19, off offset:1792
	s_and_saveexec_b64 s[20:21], s[6:7]
	s_cbranch_execz .LBB0_1787
	s_add_u32 s30, s56, s23
	v_mul_f32_e32 v1, 0x3c010204, v1
	s_addc_u32 s31, s57, s24
	global_store_dword v18, v1, s[30:31]
